# remove cooperative-groups grid sync at kernel start (xcd barrier self-synchronizes)
# speedup vs baseline: 1.0150x; 1.0150x over previous
.LBB0_6:
	s_or_b64 exec, exec, s[4:5]
.LBB0_17:
	s_load_dwordx16 s[4:19], s[0:1], 0x0
	s_add_u32 s88, s28, 0x3980000
	s_addc_u32 s89, s29, 0
	s_cmp_lt_i32 s30, 1
	s_waitcnt lgkmcnt(0)
	v_writelane_b32 v238, s4, 5
	s_nop 1
	v_writelane_b32 v238, s5, 6
	v_writelane_b32 v238, s6, 7
	v_writelane_b32 v238, s7, 8
	v_writelane_b32 v238, s8, 9
	v_writelane_b32 v238, s9, 10
	v_writelane_b32 v238, s10, 11
	v_writelane_b32 v238, s11, 12
	v_writelane_b32 v238, s12, 13
	v_writelane_b32 v238, s13, 14
	v_writelane_b32 v238, s14, 15
	v_writelane_b32 v238, s15, 16
	v_writelane_b32 v238, s16, 17
	v_writelane_b32 v238, s17, 18
	v_writelane_b32 v238, s18, 19
	v_writelane_b32 v238, s19, 20
	s_load_dwordx16 s[4:19], s[0:1], 0x40
	s_waitcnt lgkmcnt(0)
	v_writelane_b32 v238, s4, 21
	s_nop 1
	v_writelane_b32 v238, s5, 22
	v_writelane_b32 v238, s6, 23
	v_writelane_b32 v238, s7, 24
	v_writelane_b32 v238, s8, 25
	v_writelane_b32 v238, s9, 26
	v_writelane_b32 v238, s10, 27
	v_writelane_b32 v238, s11, 28
	v_writelane_b32 v238, s12, 29
	v_writelane_b32 v238, s13, 30
	v_writelane_b32 v238, s14, 31
	v_writelane_b32 v238, s15, 32
	v_writelane_b32 v238, s16, 33
	v_writelane_b32 v238, s17, 34
	v_writelane_b32 v238, s18, 35
	v_writelane_b32 v238, s19, 36
	s_load_dwordx16 s[4:19], s[0:1], 0x80
	s_waitcnt lgkmcnt(0)
	v_writelane_b32 v238, s4, 37
	s_nop 1
	v_writelane_b32 v238, s5, 38
	v_writelane_b32 v238, s6, 39
	v_writelane_b32 v238, s7, 40
	v_writelane_b32 v238, s8, 41
	v_writelane_b32 v238, s9, 42
	v_writelane_b32 v238, s10, 43
	v_writelane_b32 v238, s11, 44
	v_writelane_b32 v238, s12, 45
	v_writelane_b32 v238, s13, 46
	v_writelane_b32 v238, s14, 47
	v_writelane_b32 v238, s15, 48
	v_writelane_b32 v238, s16, 49
	v_writelane_b32 v238, s17, 50
	v_writelane_b32 v238, s18, 51
	v_writelane_b32 v238, s19, 52
	s_cselect_b64 s[10:11], -1, 0
	s_cmp_gt_i32 s30, 0
	s_cselect_b64 s[0:1], -1, 0
	s_cmp_lt_i32 s31, 1
	s_cselect_b64 s[4:5], -1, 0
	s_or_b64 s[0:1], s[0:1], s[4:5]
	s_and_b64 vcc, exec, s[0:1]
	s_cbranch_vccnz .LBB0_761
	v_bfe_u32 v2, v0, 6, 4
	v_lshl_or_b32 v1, s2, 3, v2
	s_movk_i32 s20, 0x4500
	v_and_b32_e32 v34, 63, v0
	s_lshl_b32 s3, s34, 3
	v_cmp_gt_i32_e32 vcc, s20, v1
	s_and_saveexec_b64 s[12:13], vcc
	s_cbranch_execz .LBB0_65
	v_mbcnt_lo_u32_b32 v3, -1, 0
	v_mbcnt_hi_u32_b32 v3, -1, v3
	v_and_b32_e32 v4, 64, v3
	v_add_u32_e32 v4, 64, v4
	v_xor_b32_e32 v5, 1, v3
	v_cmp_lt_i32_e64 s[0:1], v5, v4
	s_add_u32 s14, s28, 0xe600000
	v_mov_b32_e32 v37, 0
	v_cndmask_b32_e64 v5, v3, v5, s[0:1]
	v_lshlrev_b32_e32 v35, 2, v5
	v_xor_b32_e32 v5, 2, v3
	v_cmp_lt_i32_e64 s[0:1], v5, v4
	v_lshlrev_b32_e32 v36, 3, v34
	v_lshlrev_b32_e32 v2, 10, v2
	v_cndmask_b32_e64 v5, v3, v5, s[0:1]
	v_lshlrev_b32_e32 v46, 2, v5
	v_xor_b32_e32 v5, 4, v3
	v_cmp_lt_i32_e64 s[0:1], v5, v4
	s_addc_u32 s15, s29, 0
	v_cmp_ne_u32_e32 vcc, 0, v34
	v_cndmask_b32_e64 v5, v3, v5, s[0:1]
	v_lshlrev_b32_e32 v47, 2, v5
	v_xor_b32_e32 v5, 8, v3
	v_cmp_lt_i32_e64 s[0:1], v5, v4
	v_lshl_add_u64 v[38:39], s[88:89], 0, v[36:37]
	v_lshl_add_u32 v51, s2, 13, v2
	v_cndmask_b32_e64 v5, v3, v5, s[0:1]
	v_lshlrev_b32_e32 v48, 2, v5
	v_xor_b32_e32 v5, 16, v3
	v_cmp_lt_i32_e64 s[0:1], v5, v4
	s_lshl_b32 s21, s34, 14
	s_lshl_b32 s22, s34, 13
	v_cndmask_b32_e64 v5, v3, v5, s[0:1]
	v_lshlrev_b32_e32 v49, 2, v5
	v_xor_b32_e32 v5, 32, v3
	v_cmp_lt_i32_e64 s[0:1], v5, v4
	s_mov_b64 s[16:17], 0
	s_movk_i32 s23, 0x3fff
	v_cndmask_b32_e64 v3, v3, v5, s[0:1]
	v_lshlrev_b32_e32 v50, 2, v3
	s_movk_i32 s33, 0x43ff
	s_movk_i32 s35, 0x4480
	v_mov_b32_e32 v52, 0x358637bd
	s_mov_b32 s52, 0x800000
	s_movk_i32 s53, 0x44ff
	v_mov_b32_e32 v42, v1
	s_branch .LBB0_22
